# v53 plus the same rss-load hoist in the P1 sample-unit SwiGLU epilogue
# speedup vs baseline: 1.0131x; 1.0045x over previous
; __device__ __forceinline__ unsigned cvt_pk_bf16(float lo, float hi) { unsigned r; asm volatile("v_cvt_pk_bf16_f32 %0, %1, %2" : "=v"(r) : "v"(lo), "v"(hi)); return r; }
; __device__ __forceinline__ float silu_f(float x) { return x * sigmoid_f(x); }
;     __device__ __forceinline__ void operator()(const f32x4 (&acc)[2][2][4][2], const Unit& u, int wr, int wc, int fr, int fq) const {
;     ...
;             for (int m = 0; m < 4; ++m) {
;                 const int row = row0 + ai * HALF + m * 16;
;                 const float r = __builtin_amdgcn_rsqf(rss[row] * (1.f / 1024.f) + NEPS);
;                 float o[8];
; #pragma unroll
;                 for (int n = 0; n < 2; ++n)
; #pragma unroll
;                     for (int e = 0; e < 4; ++e) o[4 * n + e] = silu_f(acc[ai][0][m][n][e] * r) * (acc[ai][1][m][n][e] * r);
;                 u32x4 w; w.x = cvt_pk_bf16(o[0], o[1]); w.y = cvt_pk_bf16(o[2], o[3]); w.z = cvt_pk_bf16(o[4], o[5]); w.w = cvt_pk_bf16(o[6], o[7]);
;                 *(u32x4*)(O + (size_t)row * 2816 + col0) = w;
.LBB0_149:
	v_lshl_add_u32 v130, s23, 8, v139
	v_ashrrev_i32_e32 v131, 31, v130
	v_lshl_add_u64 v[132:133], v[130:131], 2, s[4:5]
	global_load_dword v200, v[132:133], off
	global_load_dword v201, v[132:133], off offset:64
	global_load_dword v202, v[132:133], off offset:128
	global_load_dword v203, v[132:133], off offset:192
	global_load_dword v204, v[132:133], off offset:512
	global_load_dword v205, v[132:133], off offset:576
	global_load_dword v206, v[132:133], off offset:640
	global_load_dword v207, v[132:133], off offset:704
	v_mov_b32_e32 v131, 0x358637bd
	v_mov_b32_e32 v137, v116
	v_mov_b32_e32 v116, v125
	v_mov_b32_e32 v134, v126
	v_mov_b32_e32 v135, v118
	v_mov_b32_e32 v118, v127
	v_mov_b32_e32 v126, v128
	v_mov_b32_e32 v127, v120
	v_mov_b32_e32 v120, v129
	v_mov_b32_e32 v128, v122
	v_mov_b32_e32 v129, v114
	v_mov_b32_e32 v114, v123
	v_mov_b32_e32 v136, v124
	v_or_b32_e32 v140, 16, v130
	v_lshl_or_b32 v138, s22, 7, v138
	s_movk_i32 s6, 0x1600
	v_mov_b64_e32 v[124:125], s[60:61]
	v_or_b32_e32 v122, s21, v138
	v_mov_b32_e32 v123, 0
	v_mad_i64_i32 v[138:139], s[8:9], v130, s6, v[124:125]
	v_lshlrev_b32_e32 v122, 1, v122
	v_lshl_add_u64 v[138:139], v[138:139], 0, v[122:123]
	s_waitcnt vmcnt(0)
	v_mov_b32_e32 v141, v200
	v_fmamk_f32 v141, v141, 0x3a800000, v131
	v_rsq_f32_e32 v142, v141
	v_ashrrev_i32_e32 v141, 31, v140
	v_lshl_add_u64 v[144:145], v[140:141], 2, s[4:5]
	v_pk_mul_f32 v[116:117], v[116:117], v[142:143] op_sel_hi:[1,0]
	v_pk_mul_f32 v[134:135], v[134:135], v[142:143] op_sel_hi:[1,0]
	v_pk_mul_f32 v[118:119], v[118:119], v[142:143] op_sel_hi:[1,0]
	v_pk_mul_f32 v[126:127], v[126:127], v[142:143] op_sel_hi:[1,0]
	v_pk_mul_f32 v[120:121], v[120:121], v[142:143] op_sel_hi:[1,0]
	v_pk_mul_f32 v[128:129], v[128:129], v[142:143] op_sel_hi:[1,0]
	v_pk_mul_f32 v[114:115], v[114:115], v[142:143] op_sel_hi:[1,0]
	v_pk_mul_f32 v[136:137], v[136:137], v[142:143] op_sel_hi:[1,0]
	v_mul_f32_e32 v150, 0xbfb8aa3b, v117
	v_mul_f32_e32 v141, 0xbfb8aa3b, v135
	v_mul_f32_e32 v142, 0xbfb8aa3b, v119
	v_mul_f32_e32 v143, 0xbfb8aa3b, v127
	v_mul_f32_e32 v146, 0xbfb8aa3b, v121
	v_mul_f32_e32 v147, 0xbfb8aa3b, v129
	v_mul_f32_e32 v148, 0xbfb8aa3b, v115
	v_mul_f32_e32 v149, 0xbfb8aa3b, v137
	v_exp_f32_e32 v150, v150
	v_exp_f32_e32 v141, v141
	v_exp_f32_e32 v142, v142
	v_exp_f32_e32 v143, v143
	v_exp_f32_e32 v146, v146
	v_exp_f32_e32 v147, v147
	v_exp_f32_e32 v148, v148
	v_exp_f32_e32 v149, v149
	v_add_f32_e32 v150, 1.0, v150
	v_add_f32_e32 v141, 1.0, v141
	v_add_f32_e32 v142, 1.0, v142
	v_add_f32_e32 v143, 1.0, v143
	v_add_f32_e32 v146, 1.0, v146
	v_add_f32_e32 v147, 1.0, v147
	v_add_f32_e32 v148, 1.0, v148
	v_add_f32_e32 v149, 1.0, v149
	v_rcp_f32_e32 v150, v150
	v_rcp_f32_e32 v141, v141
	v_rcp_f32_e32 v142, v142
	v_rcp_f32_e32 v143, v143
	v_rcp_f32_e32 v146, v146
	v_rcp_f32_e32 v147, v147
	v_rcp_f32_e32 v148, v148
	v_rcp_f32_e32 v149, v149
	v_mul_f32_e32 v117, v117, v150
	v_mul_f32_e32 v135, v135, v141
	v_mul_f32_e32 v119, v119, v142
	v_mul_f32_e32 v127, v127, v143
	v_mul_f32_e32 v121, v121, v146
	v_mul_f32_e32 v129, v129, v147
	v_mul_f32_e32 v115, v115, v148
	v_mul_f32_e32 v137, v137, v149
	v_mul_f32_e32 v117, v116, v117
	v_mul_f32_e32 v134, v134, v135
	v_mul_f32_e32 v118, v118, v119
	v_mul_f32_e32 v119, v126, v127
	v_mul_f32_e32 v120, v120, v121
	v_mul_f32_e32 v121, v128, v129
	v_mul_f32_e32 v126, v114, v115
	v_mul_f32_e32 v127, v136, v137
	v_cvt_pk_bf16_f32 v114, v134, v118
	v_cvt_pk_bf16_f32 v115, v119, v120
	v_cvt_pk_bf16_f32 v116, v121, v126
	v_cvt_pk_bf16_f32 v117, v127, v117
	global_store_dwordx4 v[138:139], v[114:117], off
	s_nop 0
	s_nop 0
	v_mov_b32_e32 v115, v106
	v_mov_b32_e32 v106, v111
	v_mov_b32_e32 v111, v108
	v_mov_b32_e32 v108, v113
	v_mov_b32_e32 v113, v98
	v_mov_b32_e32 v98, v103
	v_mov_b32_e32 v103, v100
	v_mov_b32_e32 v100, v105
	v_mov_b32_e32 v114, v110
	v_mov_b32_e32 v110, v112
	v_mov_b32_e32 v112, v102
	v_mov_b32_e32 v102, v104
	v_or_b32_e32 v104, 32, v130
	v_mad_i64_i32 v[116:117], s[8:9], v140, s6, v[124:125]
	v_lshl_add_u64 v[116:117], v[116:117], 0, v[122:123]
	s_waitcnt vmcnt(7)
	v_mov_b32_e32 v118, v201
	v_fmamk_f32 v105, v118, 0x3a800000, v131
	v_rsq_f32_e32 v118, v105
	v_ashrrev_i32_e32 v105, 31, v104
	v_lshl_add_u64 v[120:121], v[104:105], 2, s[4:5]
	v_pk_mul_f32 v[100:101], v[100:101], v[118:119] op_sel_hi:[1,0]
	v_pk_mul_f32 v[114:115], v[114:115], v[118:119] op_sel_hi:[1,0]
	v_pk_mul_f32 v[106:107], v[106:107], v[118:119] op_sel_hi:[1,0]
	v_pk_mul_f32 v[110:111], v[110:111], v[118:119] op_sel_hi:[1,0]
	v_pk_mul_f32 v[108:109], v[108:109], v[118:119] op_sel_hi:[1,0]
	v_pk_mul_f32 v[112:113], v[112:113], v[118:119] op_sel_hi:[1,0]
	v_pk_mul_f32 v[98:99], v[98:99], v[118:119] op_sel_hi:[1,0]
	v_pk_mul_f32 v[102:103], v[102:103], v[118:119] op_sel_hi:[1,0]
	v_mul_f32_e32 v134, 0xbfb8aa3b, v101
	v_mul_f32_e32 v105, 0xbfb8aa3b, v115
	v_mul_f32_e32 v118, 0xbfb8aa3b, v107
	v_mul_f32_e32 v119, 0xbfb8aa3b, v111
	v_mul_f32_e32 v126, 0xbfb8aa3b, v109
	v_mul_f32_e32 v127, 0xbfb8aa3b, v113
	v_mul_f32_e32 v128, 0xbfb8aa3b, v99
	v_mul_f32_e32 v129, 0xbfb8aa3b, v103
	v_exp_f32_e32 v134, v134
	v_exp_f32_e32 v105, v105
	v_exp_f32_e32 v118, v118
	v_exp_f32_e32 v119, v119
	v_exp_f32_e32 v126, v126
	v_exp_f32_e32 v127, v127
	v_exp_f32_e32 v128, v128
	v_exp_f32_e32 v129, v129
	v_add_f32_e32 v134, 1.0, v134
	v_add_f32_e32 v105, 1.0, v105
	v_add_f32_e32 v118, 1.0, v118
	v_add_f32_e32 v119, 1.0, v119
	v_add_f32_e32 v126, 1.0, v126
	v_add_f32_e32 v127, 1.0, v127
	v_add_f32_e32 v128, 1.0, v128
	v_add_f32_e32 v129, 1.0, v129
	v_rcp_f32_e32 v134, v134
	v_rcp_f32_e32 v105, v105
	v_rcp_f32_e32 v118, v118
	v_rcp_f32_e32 v119, v119
	v_rcp_f32_e32 v126, v126
	v_rcp_f32_e32 v127, v127
	v_rcp_f32_e32 v128, v128
	v_rcp_f32_e32 v129, v129
	v_mul_f32_e32 v101, v101, v134
	v_mul_f32_e32 v105, v115, v105
	v_mul_f32_e32 v107, v107, v118
	v_mul_f32_e32 v111, v111, v119
	v_mul_f32_e32 v109, v109, v126
	v_mul_f32_e32 v113, v113, v127
	v_mul_f32_e32 v99, v99, v128
	v_mul_f32_e32 v103, v103, v129
	v_mul_f32_e32 v101, v100, v101
	v_mul_f32_e32 v105, v114, v105
	v_mul_f32_e32 v106, v106, v107
	v_mul_f32_e32 v107, v110, v111
	v_mul_f32_e32 v108, v108, v109
	v_mul_f32_e32 v109, v112, v113
	v_mul_f32_e32 v110, v98, v99
	v_mul_f32_e32 v102, v102, v103
	v_cvt_pk_bf16_f32 v98, v105, v106
	v_cvt_pk_bf16_f32 v99, v107, v108
	v_cvt_pk_bf16_f32 v100, v109, v110
	v_cvt_pk_bf16_f32 v101, v102, v101
	global_store_dwordx4 v[116:117], v[98:101], off
	s_nop 0
	s_nop 0
	v_mov_b32_e32 v99, v90
	v_mov_b32_e32 v90, v95
	v_mov_b32_e32 v95, v92
	v_mov_b32_e32 v92, v97
	v_mov_b32_e32 v97, v82
	v_mov_b32_e32 v82, v87
	v_mov_b32_e32 v87, v84
	v_mov_b32_e32 v84, v89
	v_mov_b32_e32 v98, v94
	v_mov_b32_e32 v94, v96
	v_mov_b32_e32 v96, v86
	v_mov_b32_e32 v86, v88
	v_or_b32_e32 v88, 48, v130
	v_mad_i64_i32 v[100:101], s[8:9], v104, s6, v[124:125]
	v_lshl_add_u64 v[100:101], v[100:101], 0, v[122:123]
	s_waitcnt vmcnt(7)
; __device__ __forceinline__ unsigned cvt_pk_bf16(float lo, float hi) { unsigned r; asm volatile("v_cvt_pk_bf16_f32 %0, %1, %2" : "=v"(r) : "v"(lo), "v"(hi)); return r; }
; __device__ __forceinline__ float silu_f(float x) { return x * sigmoid_f(x); }
;     __device__ __forceinline__ void operator()(const f32x4 (&acc)[2][2][4][2], const Unit& u, int wr, int wc, int fr, int fq) const {
;     ...
;             for (int m = 0; m < 4; ++m) {
;                 const int row = row0 + ai * HALF + m * 16;
;                 const float r = __builtin_amdgcn_rsqf(rss[row] * (1.f / 1024.f) + NEPS);
;                 float o[8];
; #pragma unroll
;                 for (int n = 0; n < 2; ++n)
; #pragma unroll
;                     for (int e = 0; e < 4; ++e) o[4 * n + e] = silu_f(acc[ai][0][m][n][e] * r) * (acc[ai][1][m][n][e] * r);
;                 u32x4 w; w.x = cvt_pk_bf16(o[0], o[1]); w.y = cvt_pk_bf16(o[2], o[3]); w.z = cvt_pk_bf16(o[4], o[5]); w.w = cvt_pk_bf16(o[6], o[7]);
;                 *(u32x4*)(O + (size_t)row * 2816 + col0) = w;
	v_mov_b32_e32 v102, v202
	v_fmamk_f32 v89, v102, 0x3a800000, v131
	v_rsq_f32_e32 v102, v89
	v_ashrrev_i32_e32 v89, 31, v88
	v_lshl_add_u64 v[104:105], v[88:89], 2, s[4:5]
	v_pk_mul_f32 v[84:85], v[84:85], v[102:103] op_sel_hi:[1,0]
	v_pk_mul_f32 v[98:99], v[98:99], v[102:103] op_sel_hi:[1,0]
	v_pk_mul_f32 v[90:91], v[90:91], v[102:103] op_sel_hi:[1,0]
	v_pk_mul_f32 v[94:95], v[94:95], v[102:103] op_sel_hi:[1,0]
	v_pk_mul_f32 v[92:93], v[92:93], v[102:103] op_sel_hi:[1,0]
	v_pk_mul_f32 v[96:97], v[96:97], v[102:103] op_sel_hi:[1,0]
	v_pk_mul_f32 v[82:83], v[82:83], v[102:103] op_sel_hi:[1,0]
	v_pk_mul_f32 v[86:87], v[86:87], v[102:103] op_sel_hi:[1,0]
	v_mul_f32_e32 v110, 0xbfb8aa3b, v85
	v_mul_f32_e32 v89, 0xbfb8aa3b, v99
	v_mul_f32_e32 v102, 0xbfb8aa3b, v91
	v_mul_f32_e32 v103, 0xbfb8aa3b, v95
	v_mul_f32_e32 v106, 0xbfb8aa3b, v93
	v_mul_f32_e32 v107, 0xbfb8aa3b, v97
	v_mul_f32_e32 v108, 0xbfb8aa3b, v83
	v_mul_f32_e32 v109, 0xbfb8aa3b, v87
	v_exp_f32_e32 v110, v110
	v_exp_f32_e32 v89, v89
	v_exp_f32_e32 v102, v102
	v_exp_f32_e32 v103, v103
	v_exp_f32_e32 v106, v106
	v_exp_f32_e32 v107, v107
	v_exp_f32_e32 v108, v108
	v_exp_f32_e32 v109, v109
	v_add_f32_e32 v110, 1.0, v110
	v_add_f32_e32 v89, 1.0, v89
	v_add_f32_e32 v102, 1.0, v102
	v_add_f32_e32 v103, 1.0, v103
	v_add_f32_e32 v106, 1.0, v106
	v_add_f32_e32 v107, 1.0, v107
	v_add_f32_e32 v108, 1.0, v108
	v_add_f32_e32 v109, 1.0, v109
	v_rcp_f32_e32 v110, v110
	v_rcp_f32_e32 v89, v89
	v_rcp_f32_e32 v102, v102
	v_rcp_f32_e32 v103, v103
	v_rcp_f32_e32 v106, v106
	v_rcp_f32_e32 v107, v107
	v_rcp_f32_e32 v108, v108
	v_rcp_f32_e32 v109, v109
	v_mul_f32_e32 v85, v85, v110
	v_mul_f32_e32 v89, v99, v89
	v_mul_f32_e32 v91, v91, v102
	v_mul_f32_e32 v95, v95, v103
	v_mul_f32_e32 v93, v93, v106
	v_mul_f32_e32 v97, v97, v107
	v_mul_f32_e32 v83, v83, v108
	v_mul_f32_e32 v87, v87, v109
	v_mul_f32_e32 v85, v84, v85
	v_mul_f32_e32 v89, v98, v89
	v_mul_f32_e32 v90, v90, v91
	v_mul_f32_e32 v91, v94, v95
	v_mul_f32_e32 v92, v92, v93
	v_mul_f32_e32 v93, v96, v97
	v_mul_f32_e32 v94, v82, v83
	v_mul_f32_e32 v86, v86, v87
	v_cvt_pk_bf16_f32 v82, v89, v90
	v_cvt_pk_bf16_f32 v83, v91, v92
	v_cvt_pk_bf16_f32 v84, v93, v94
	v_cvt_pk_bf16_f32 v85, v86, v85
	global_store_dwordx4 v[100:101], v[82:85], off
	s_nop 0
	s_nop 0
	v_mov_b32_e32 v82, v78
	v_mov_b32_e32 v78, v80
	v_mov_b32_e32 v80, v66
	v_mov_b32_e32 v66, v68
	v_mov_b32_e32 v83, v74
	v_mov_b32_e32 v74, v79
	v_mov_b32_e32 v79, v76
	v_mov_b32_e32 v76, v81
	v_mov_b32_e32 v81, v70
	v_mov_b32_e32 v70, v67
	v_mov_b32_e32 v67, v72
	v_mov_b32_e32 v72, v69
	s_waitcnt vmcnt(7)
	v_mov_b32_e32 v84, v203
	v_fmamk_f32 v68, v84, 0x3a800000, v131
	v_rsq_f32_e32 v68, v68
	v_mad_i64_i32 v[84:85], s[4:5], v88, s6, v[124:125]
	v_lshl_add_u64 v[84:85], v[84:85], 0, v[122:123]
	v_pk_mul_f32 v[82:83], v[82:83], v[68:69] op_sel_hi:[1,0]
	v_pk_mul_f32 v[74:75], v[74:75], v[68:69] op_sel_hi:[1,0]
	v_pk_mul_f32 v[78:79], v[78:79], v[68:69] op_sel_hi:[1,0]
	v_pk_mul_f32 v[76:77], v[76:77], v[68:69] op_sel_hi:[1,0]
	v_pk_mul_f32 v[80:81], v[80:81], v[68:69] op_sel_hi:[1,0]
	v_pk_mul_f32 v[70:71], v[70:71], v[68:69] op_sel_hi:[1,0]
	v_pk_mul_f32 v[66:67], v[66:67], v[68:69] op_sel_hi:[1,0]
	v_pk_mul_f32 v[68:69], v[72:73], v[68:69] op_sel_hi:[1,0]
	v_mul_f32_e32 v72, 0xbfb8aa3b, v83
	v_mul_f32_e32 v91, 0xbfb8aa3b, v69
	v_mul_f32_e32 v73, 0xbfb8aa3b, v75
	v_mul_f32_e32 v86, 0xbfb8aa3b, v79
	v_mul_f32_e32 v87, 0xbfb8aa3b, v77
	v_mul_f32_e32 v88, 0xbfb8aa3b, v81
	v_mul_f32_e32 v89, 0xbfb8aa3b, v71
	v_mul_f32_e32 v90, 0xbfb8aa3b, v67
	v_exp_f32_e32 v91, v91
	v_exp_f32_e32 v72, v72
	v_exp_f32_e32 v73, v73
	v_exp_f32_e32 v86, v86
	v_exp_f32_e32 v87, v87
	v_exp_f32_e32 v88, v88
	v_exp_f32_e32 v89, v89
	v_exp_f32_e32 v90, v90
	v_add_f32_e32 v91, 1.0, v91
	v_add_f32_e32 v72, 1.0, v72
	v_add_f32_e32 v73, 1.0, v73
	v_add_f32_e32 v86, 1.0, v86
	v_add_f32_e32 v87, 1.0, v87
	v_add_f32_e32 v88, 1.0, v88
	v_add_f32_e32 v89, 1.0, v89
	v_add_f32_e32 v90, 1.0, v90
	v_rcp_f32_e32 v91, v91
	v_rcp_f32_e32 v72, v72
	v_rcp_f32_e32 v73, v73
	v_rcp_f32_e32 v86, v86
	v_rcp_f32_e32 v87, v87
	v_rcp_f32_e32 v88, v88
	v_rcp_f32_e32 v89, v89
	v_rcp_f32_e32 v90, v90
	v_mul_f32_e32 v69, v69, v91
	v_mul_f32_e32 v72, v83, v72
	v_mul_f32_e32 v73, v75, v73
	v_mul_f32_e32 v75, v79, v86
	v_mul_f32_e32 v77, v77, v87
	v_mul_f32_e32 v79, v81, v88
	v_mul_f32_e32 v71, v71, v89
	v_mul_f32_e32 v67, v67, v90
	v_mul_f32_e32 v69, v68, v69
	v_mul_f32_e32 v72, v82, v72
	v_mul_f32_e32 v73, v74, v73
	v_mul_f32_e32 v74, v78, v75
	v_mul_f32_e32 v75, v76, v77
	v_mul_f32_e32 v76, v80, v79
	v_mul_f32_e32 v70, v70, v71
	v_mul_f32_e32 v71, v66, v67
	v_cvt_pk_bf16_f32 v66, v72, v73
	v_cvt_pk_bf16_f32 v67, v74, v75
	v_cvt_pk_bf16_f32 v68, v76, v70
	v_cvt_pk_bf16_f32 v69, v71, v69
	global_store_dwordx4 v[84:85], v[66:69], off
	s_nop 0
	s_nop 0
	v_mov_b32_e32 v66, v62
	v_mov_b32_e32 v62, v64
	v_mov_b32_e32 v64, v50
	v_mov_b32_e32 v50, v52
	v_mov_b32_e32 v67, v58
	v_mov_b32_e32 v58, v63
	v_mov_b32_e32 v63, v60
	v_mov_b32_e32 v60, v65
	v_mov_b32_e32 v65, v54
	v_mov_b32_e32 v54, v51
	v_mov_b32_e32 v51, v56
	v_mov_b32_e32 v56, v53
	v_add_u32_e32 v53, 0x80, v130
	s_waitcnt vmcnt(7)
; __device__ __forceinline__ unsigned cvt_pk_bf16(float lo, float hi) { unsigned r; asm volatile("v_cvt_pk_bf16_f32 %0, %1, %2" : "=v"(r) : "v"(lo), "v"(hi)); return r; }
; __device__ __forceinline__ float silu_f(float x) { return x * sigmoid_f(x); }
;     __device__ __forceinline__ void operator()(const f32x4 (&acc)[2][2][4][2], const Unit& u, int wr, int wc, int fr, int fq) const {
;     ...
;             for (int m = 0; m < 4; ++m) {
;                 const int row = row0 + ai * HALF + m * 16;
;                 const float r = __builtin_amdgcn_rsqf(rss[row] * (1.f / 1024.f) + NEPS);
;                 float o[8];
; #pragma unroll
;                 for (int n = 0; n < 2; ++n)
; #pragma unroll
;                     for (int e = 0; e < 4; ++e) o[4 * n + e] = silu_f(acc[ai][0][m][n][e] * r) * (acc[ai][1][m][n][e] * r);
;                 u32x4 w; w.x = cvt_pk_bf16(o[0], o[1]); w.y = cvt_pk_bf16(o[2], o[3]); w.z = cvt_pk_bf16(o[4], o[5]); w.w = cvt_pk_bf16(o[6], o[7]);
;                 *(u32x4*)(O + (size_t)row * 2816 + col0) = w;
	v_mov_b32_e32 v68, v204
	v_fmamk_f32 v52, v68, 0x3a800000, v131
	v_rsq_f32_e32 v52, v52
	v_mad_i64_i32 v[68:69], s[4:5], v53, s6, v[124:125]
	v_lshl_add_u64 v[68:69], v[68:69], 0, v[122:123]
	v_pk_mul_f32 v[66:67], v[66:67], v[52:53] op_sel_hi:[1,0]
	v_pk_mul_f32 v[58:59], v[58:59], v[52:53] op_sel_hi:[1,0]
	v_pk_mul_f32 v[62:63], v[62:63], v[52:53] op_sel_hi:[1,0]
	v_pk_mul_f32 v[60:61], v[60:61], v[52:53] op_sel_hi:[1,0]
	v_pk_mul_f32 v[64:65], v[64:65], v[52:53] op_sel_hi:[1,0]
	v_pk_mul_f32 v[54:55], v[54:55], v[52:53] op_sel_hi:[1,0]
	v_pk_mul_f32 v[50:51], v[50:51], v[52:53] op_sel_hi:[1,0]
	v_pk_mul_f32 v[52:53], v[56:57], v[52:53] op_sel_hi:[1,0]
	v_mul_f32_e32 v56, 0xbfb8aa3b, v67
	v_mul_f32_e32 v75, 0xbfb8aa3b, v53
	v_mul_f32_e32 v57, 0xbfb8aa3b, v59
	v_mul_f32_e32 v70, 0xbfb8aa3b, v63
	v_mul_f32_e32 v71, 0xbfb8aa3b, v61
	v_mul_f32_e32 v72, 0xbfb8aa3b, v65
	v_mul_f32_e32 v73, 0xbfb8aa3b, v55
	v_mul_f32_e32 v74, 0xbfb8aa3b, v51
	v_exp_f32_e32 v75, v75
	v_exp_f32_e32 v56, v56
	v_exp_f32_e32 v57, v57
	v_exp_f32_e32 v70, v70
	v_exp_f32_e32 v71, v71
	v_exp_f32_e32 v72, v72
	v_exp_f32_e32 v73, v73
	v_exp_f32_e32 v74, v74
	v_add_f32_e32 v75, 1.0, v75
	v_add_f32_e32 v56, 1.0, v56
	v_add_f32_e32 v57, 1.0, v57
	v_add_f32_e32 v70, 1.0, v70
	v_add_f32_e32 v71, 1.0, v71
	v_add_f32_e32 v72, 1.0, v72
	v_add_f32_e32 v73, 1.0, v73
	v_add_f32_e32 v74, 1.0, v74
	v_rcp_f32_e32 v75, v75
	v_rcp_f32_e32 v56, v56
	v_rcp_f32_e32 v57, v57
	v_rcp_f32_e32 v70, v70
	v_rcp_f32_e32 v71, v71
	v_rcp_f32_e32 v72, v72
	v_rcp_f32_e32 v73, v73
	v_rcp_f32_e32 v74, v74
	v_mul_f32_e32 v53, v53, v75
	v_mul_f32_e32 v56, v67, v56
	v_mul_f32_e32 v57, v59, v57
	v_mul_f32_e32 v59, v63, v70
	v_mul_f32_e32 v61, v61, v71
	v_mul_f32_e32 v63, v65, v72
	v_mul_f32_e32 v55, v55, v73
	v_mul_f32_e32 v51, v51, v74
	v_mul_f32_e32 v53, v52, v53
	v_mul_f32_e32 v56, v66, v56
	v_mul_f32_e32 v57, v58, v57
	v_mul_f32_e32 v58, v62, v59
	v_mul_f32_e32 v59, v60, v61
	v_mul_f32_e32 v60, v64, v63
	v_mul_f32_e32 v54, v54, v55
	v_mul_f32_e32 v55, v50, v51
	v_cvt_pk_bf16_f32 v50, v56, v57
	v_cvt_pk_bf16_f32 v51, v58, v59
	v_cvt_pk_bf16_f32 v52, v60, v54
	v_cvt_pk_bf16_f32 v53, v55, v53
	global_store_dwordx4 v[68:69], v[50:53], off
	s_nop 0
	s_nop 0
	v_mov_b32_e32 v50, v46
	v_mov_b32_e32 v46, v48
	v_mov_b32_e32 v48, v34
	v_mov_b32_e32 v34, v36
	v_mov_b32_e32 v51, v42
	v_mov_b32_e32 v42, v47
	v_mov_b32_e32 v47, v44
	v_mov_b32_e32 v44, v49
	v_mov_b32_e32 v49, v38
	v_mov_b32_e32 v38, v35
	v_mov_b32_e32 v35, v40
	v_mov_b32_e32 v40, v37
	v_add_u32_e32 v37, 0x90, v130
	s_waitcnt vmcnt(7)
	v_mov_b32_e32 v52, v205
	v_fmamk_f32 v36, v52, 0x3a800000, v131
	v_rsq_f32_e32 v36, v36
	v_mad_i64_i32 v[52:53], s[4:5], v37, s6, v[124:125]
	v_lshl_add_u64 v[52:53], v[52:53], 0, v[122:123]
	v_pk_mul_f32 v[50:51], v[50:51], v[36:37] op_sel_hi:[1,0]
	v_pk_mul_f32 v[42:43], v[42:43], v[36:37] op_sel_hi:[1,0]
	v_pk_mul_f32 v[46:47], v[46:47], v[36:37] op_sel_hi:[1,0]
	v_pk_mul_f32 v[44:45], v[44:45], v[36:37] op_sel_hi:[1,0]
	v_pk_mul_f32 v[48:49], v[48:49], v[36:37] op_sel_hi:[1,0]
	v_pk_mul_f32 v[38:39], v[38:39], v[36:37] op_sel_hi:[1,0]
	v_pk_mul_f32 v[34:35], v[34:35], v[36:37] op_sel_hi:[1,0]
	v_pk_mul_f32 v[36:37], v[40:41], v[36:37] op_sel_hi:[1,0]
	v_mul_f32_e32 v40, 0xbfb8aa3b, v51
	v_mul_f32_e32 v59, 0xbfb8aa3b, v37
	v_mul_f32_e32 v41, 0xbfb8aa3b, v43
	v_mul_f32_e32 v54, 0xbfb8aa3b, v47
	v_mul_f32_e32 v55, 0xbfb8aa3b, v45
	v_mul_f32_e32 v56, 0xbfb8aa3b, v49
	v_mul_f32_e32 v57, 0xbfb8aa3b, v39
	v_mul_f32_e32 v58, 0xbfb8aa3b, v35
	v_exp_f32_e32 v59, v59
	v_exp_f32_e32 v40, v40
	v_exp_f32_e32 v41, v41
	v_exp_f32_e32 v54, v54
	v_exp_f32_e32 v55, v55
	v_exp_f32_e32 v56, v56
	v_exp_f32_e32 v57, v57
	v_exp_f32_e32 v58, v58
	v_add_f32_e32 v59, 1.0, v59
	v_add_f32_e32 v40, 1.0, v40
	v_add_f32_e32 v41, 1.0, v41
	v_add_f32_e32 v54, 1.0, v54
	v_add_f32_e32 v55, 1.0, v55
	v_add_f32_e32 v56, 1.0, v56
	v_add_f32_e32 v57, 1.0, v57
	v_add_f32_e32 v58, 1.0, v58
	v_rcp_f32_e32 v59, v59
	v_rcp_f32_e32 v40, v40
	v_rcp_f32_e32 v41, v41
	v_rcp_f32_e32 v54, v54
	v_rcp_f32_e32 v55, v55
	v_rcp_f32_e32 v56, v56
	v_rcp_f32_e32 v57, v57
	v_rcp_f32_e32 v58, v58
	v_mul_f32_e32 v37, v37, v59
	v_mul_f32_e32 v40, v51, v40
	v_mul_f32_e32 v41, v43, v41
	v_mul_f32_e32 v43, v47, v54
	v_mul_f32_e32 v45, v45, v55
	v_mul_f32_e32 v47, v49, v56
	v_mul_f32_e32 v39, v39, v57
	v_mul_f32_e32 v35, v35, v58
	v_mul_f32_e32 v37, v36, v37
	v_mul_f32_e32 v40, v50, v40
	v_mul_f32_e32 v41, v42, v41
	v_mul_f32_e32 v42, v46, v43
	v_mul_f32_e32 v43, v44, v45
	v_mul_f32_e32 v44, v48, v47
	v_mul_f32_e32 v38, v38, v39
	v_mul_f32_e32 v39, v34, v35
	v_cvt_pk_bf16_f32 v34, v40, v41
	v_cvt_pk_bf16_f32 v35, v42, v43
	v_cvt_pk_bf16_f32 v36, v44, v38
	v_cvt_pk_bf16_f32 v37, v39, v37
	global_store_dwordx4 v[52:53], v[34:37], off
	s_nop 0
	s_nop 0
	v_mov_b32_e32 v34, v30
	v_mov_b32_e32 v30, v32
	v_mov_b32_e32 v32, v18
	v_mov_b32_e32 v18, v20
	v_mov_b32_e32 v35, v26
	v_mov_b32_e32 v26, v31
	v_mov_b32_e32 v31, v28
	v_mov_b32_e32 v28, v33
	v_mov_b32_e32 v33, v22
	v_mov_b32_e32 v22, v19
	v_mov_b32_e32 v19, v24
	v_mov_b32_e32 v24, v21
	v_add_u32_e32 v21, 0xa0, v130
	s_waitcnt vmcnt(7)
; __device__ __forceinline__ unsigned cvt_pk_bf16(float lo, float hi) { unsigned r; asm volatile("v_cvt_pk_bf16_f32 %0, %1, %2" : "=v"(r) : "v"(lo), "v"(hi)); return r; }
; __device__ __forceinline__ float silu_f(float x) { return x * sigmoid_f(x); }
;     __device__ __forceinline__ void operator()(const f32x4 (&acc)[2][2][4][2], const Unit& u, int wr, int wc, int fr, int fq) const {
;     ...
;             for (int m = 0; m < 4; ++m) {
;                 const int row = row0 + ai * HALF + m * 16;
;                 const float r = __builtin_amdgcn_rsqf(rss[row] * (1.f / 1024.f) + NEPS);
;                 float o[8];
; #pragma unroll
;                 for (int n = 0; n < 2; ++n)
; #pragma unroll
;                     for (int e = 0; e < 4; ++e) o[4 * n + e] = silu_f(acc[ai][0][m][n][e] * r) * (acc[ai][1][m][n][e] * r);
;                 u32x4 w; w.x = cvt_pk_bf16(o[0], o[1]); w.y = cvt_pk_bf16(o[2], o[3]); w.z = cvt_pk_bf16(o[4], o[5]); w.w = cvt_pk_bf16(o[6], o[7]);
;                 *(u32x4*)(O + (size_t)row * 2816 + col0) = w;
	v_mov_b32_e32 v36, v206
	v_fmamk_f32 v20, v36, 0x3a800000, v131
	v_rsq_f32_e32 v20, v20
	v_mad_i64_i32 v[36:37], s[4:5], v21, s6, v[124:125]
	v_lshl_add_u64 v[36:37], v[36:37], 0, v[122:123]
	v_pk_mul_f32 v[34:35], v[34:35], v[20:21] op_sel_hi:[1,0]
	v_pk_mul_f32 v[26:27], v[26:27], v[20:21] op_sel_hi:[1,0]
	v_pk_mul_f32 v[30:31], v[30:31], v[20:21] op_sel_hi:[1,0]
	v_pk_mul_f32 v[28:29], v[28:29], v[20:21] op_sel_hi:[1,0]
	v_pk_mul_f32 v[32:33], v[32:33], v[20:21] op_sel_hi:[1,0]
	v_pk_mul_f32 v[22:23], v[22:23], v[20:21] op_sel_hi:[1,0]
	v_pk_mul_f32 v[18:19], v[18:19], v[20:21] op_sel_hi:[1,0]
	v_pk_mul_f32 v[20:21], v[24:25], v[20:21] op_sel_hi:[1,0]
	v_mul_f32_e32 v24, 0xbfb8aa3b, v35
	v_mul_f32_e32 v43, 0xbfb8aa3b, v21
	v_mul_f32_e32 v25, 0xbfb8aa3b, v27
	v_mul_f32_e32 v38, 0xbfb8aa3b, v31
	v_mul_f32_e32 v39, 0xbfb8aa3b, v29
	v_mul_f32_e32 v40, 0xbfb8aa3b, v33
	v_mul_f32_e32 v41, 0xbfb8aa3b, v23
	v_mul_f32_e32 v42, 0xbfb8aa3b, v19
	v_exp_f32_e32 v43, v43
	v_exp_f32_e32 v24, v24
	v_exp_f32_e32 v25, v25
	v_exp_f32_e32 v38, v38
	v_exp_f32_e32 v39, v39
	v_exp_f32_e32 v40, v40
	v_exp_f32_e32 v41, v41
	v_exp_f32_e32 v42, v42
	v_add_f32_e32 v43, 1.0, v43
	v_add_f32_e32 v24, 1.0, v24
	v_add_f32_e32 v25, 1.0, v25
	v_add_f32_e32 v38, 1.0, v38
	v_add_f32_e32 v39, 1.0, v39
	v_add_f32_e32 v40, 1.0, v40
	v_add_f32_e32 v41, 1.0, v41
	v_add_f32_e32 v42, 1.0, v42
	v_rcp_f32_e32 v43, v43
	v_rcp_f32_e32 v24, v24
	v_rcp_f32_e32 v25, v25
	v_rcp_f32_e32 v38, v38
	v_rcp_f32_e32 v39, v39
	v_rcp_f32_e32 v40, v40
	v_rcp_f32_e32 v41, v41
	v_rcp_f32_e32 v42, v42
	v_mul_f32_e32 v21, v21, v43
	v_mul_f32_e32 v24, v35, v24
	v_mul_f32_e32 v25, v27, v25
	v_mul_f32_e32 v27, v31, v38
	v_mul_f32_e32 v29, v29, v39
	v_mul_f32_e32 v31, v33, v40
	v_mul_f32_e32 v23, v23, v41
	v_mul_f32_e32 v19, v19, v42
	v_mul_f32_e32 v21, v20, v21
	v_mul_f32_e32 v24, v34, v24
	v_mul_f32_e32 v25, v26, v25
	v_mul_f32_e32 v26, v30, v27
	v_mul_f32_e32 v27, v28, v29
	v_mul_f32_e32 v28, v32, v31
	v_mul_f32_e32 v22, v22, v23
	v_mul_f32_e32 v23, v18, v19
	v_cvt_pk_bf16_f32 v18, v24, v25
	v_cvt_pk_bf16_f32 v19, v26, v27
	v_cvt_pk_bf16_f32 v20, v28, v22
	v_cvt_pk_bf16_f32 v21, v23, v21
	global_store_dwordx4 v[36:37], v[18:21], off
	s_nop 0
	s_waitcnt vmcnt(7)
	v_mov_b32_e32 v20, v207
	v_fmac_f32_e32 v131, 0x3a800000, v20
	v_mov_b32_e32 v18, v14
	v_mov_b32_e32 v14, v16
	v_mov_b32_e32 v16, v2
	v_mov_b32_e32 v2, v4
	v_rsq_f32_e32 v4, v131
	v_mov_b32_e32 v19, v10
	v_mov_b32_e32 v10, v15
	v_mov_b32_e32 v15, v12
	v_mov_b32_e32 v12, v17
	v_mov_b32_e32 v17, v6
	v_mov_b32_e32 v6, v3
	v_mov_b32_e32 v3, v8
	v_mov_b32_e32 v8, v5
	v_add_u32_e32 v5, 0xb0, v130
	v_mad_i64_i32 v[20:21], s[4:5], v5, s6, v[124:125]
	v_pk_mul_f32 v[18:19], v[18:19], v[4:5] op_sel_hi:[1,0]
	v_pk_mul_f32 v[10:11], v[10:11], v[4:5] op_sel_hi:[1,0]
	v_pk_mul_f32 v[14:15], v[14:15], v[4:5] op_sel_hi:[1,0]
	v_pk_mul_f32 v[12:13], v[12:13], v[4:5] op_sel_hi:[1,0]
	v_pk_mul_f32 v[16:17], v[16:17], v[4:5] op_sel_hi:[1,0]
	v_pk_mul_f32 v[6:7], v[6:7], v[4:5] op_sel_hi:[1,0]
	v_pk_mul_f32 v[2:3], v[2:3], v[4:5] op_sel_hi:[1,0]
	v_pk_mul_f32 v[4:5], v[8:9], v[4:5] op_sel_hi:[1,0]
	v_mul_f32_e32 v25, 0xbfb8aa3b, v7
	v_mul_f32_e32 v26, 0xbfb8aa3b, v3
	v_mul_f32_e32 v27, 0xbfb8aa3b, v5
	v_mul_f32_e32 v8, 0xbfb8aa3b, v19
	v_mul_f32_e32 v9, 0xbfb8aa3b, v11
	v_mul_f32_e32 v22, 0xbfb8aa3b, v15
	v_mul_f32_e32 v23, 0xbfb8aa3b, v13
	v_mul_f32_e32 v24, 0xbfb8aa3b, v17
	v_exp_f32_e32 v25, v25
	v_exp_f32_e32 v26, v26
	v_exp_f32_e32 v27, v27
	v_exp_f32_e32 v8, v8
	v_exp_f32_e32 v9, v9
	v_exp_f32_e32 v22, v22
	v_exp_f32_e32 v23, v23
	v_exp_f32_e32 v24, v24
	v_add_f32_e32 v25, 1.0, v25
	v_add_f32_e32 v26, 1.0, v26
	v_add_f32_e32 v27, 1.0, v27
	v_add_f32_e32 v8, 1.0, v8
	v_add_f32_e32 v9, 1.0, v9
	v_add_f32_e32 v22, 1.0, v22
	v_add_f32_e32 v23, 1.0, v23
	v_add_f32_e32 v24, 1.0, v24
	v_rcp_f32_e32 v25, v25
	v_rcp_f32_e32 v26, v26
	v_rcp_f32_e32 v27, v27
	v_rcp_f32_e32 v8, v8
	v_rcp_f32_e32 v9, v9
	v_rcp_f32_e32 v22, v22
	v_rcp_f32_e32 v23, v23
	v_rcp_f32_e32 v24, v24
	v_mul_f32_e32 v7, v7, v25
	v_mul_f32_e32 v3, v3, v26
	v_mul_f32_e32 v5, v5, v27
	v_mul_f32_e32 v8, v19, v8
	v_mul_f32_e32 v9, v11, v9
	v_mul_f32_e32 v11, v15, v22
	v_mul_f32_e32 v13, v13, v23
	v_mul_f32_e32 v15, v17, v24
	v_mul_f32_e32 v6, v6, v7
	v_mul_f32_e32 v7, v2, v3
	v_mul_f32_e32 v5, v4, v5
	v_mul_f32_e32 v8, v18, v8
	v_mul_f32_e32 v9, v10, v9
	v_mul_f32_e32 v10, v14, v11
	v_mul_f32_e32 v11, v12, v13
	v_mul_f32_e32 v12, v16, v15
	v_cvt_pk_bf16_f32 v2, v8, v9
	v_cvt_pk_bf16_f32 v3, v10, v11
	v_cvt_pk_bf16_f32 v4, v12, v6
	v_cvt_pk_bf16_f32 v5, v7, v5
	v_lshl_add_u64 v[6:7], v[20:21], 0, v[122:123]
	global_store_dwordx4 v[6:7], v[2:5], off
	s_waitcnt vmcnt(0)
	s_barrier
